# retention gating: counted waits no longer force the step's first output store to retire (vmcnt 7 instead of 6); on top of v10
# baseline (speedup 1.0000x reference)
; __device__ __forceinline__ unsigned cvt_pk_bf16(float lo, float hi) { unsigned r; asm volatile("v_cvt_pk_bf16_f32 %0, %1, %2" : "=v"(r) : "v"(lo), "v"(hi)); return r; }
; __device__ __forceinline__ float bf_lo(unsigned u) { return __uint_as_float(u << 16); }
; __device__ __forceinline__ float bf_hi(unsigned u) { return __uint_as_float(u & 0xffff0000u); }
; __device__ __forceinline__ float silu_f(float a) { return a * __builtin_amdgcn_rcpf(1.0f + __expf(-a)); }
; __device__ __forceinline__ void retention_item(LAS unsigned char* lds, const Params& p, int item) {
;     ...
;             float sm = 0.f;
; #pragma unroll
;             for (int eb = 0; eb < 8; ++eb) sm += (accO[eb][0] + accO[eb][1]) + (accO[eb][2] + accO[eb][3]);
;             sm += __shfl_xor(sm, 16); sm += __shfl_xor(sm, 32);
;             const float mean = sm * (1.0f / 128.0f);
;             float vq = 0.f;
; #pragma unroll
;             for (int eb = 0; eb < 8; ++eb) { const f32x4 d = accO[eb] - mean; vq += (d[0] * d[0] + d[1] * d[1]) + (d[2] * d[2] + d[3] * d[3]); }
;             vq += __shfl_xor(vq, 16); vq += __shfl_xor(vq, 32);
;             const float rstd = rsqrtf(vq * (1.0f / 128.0f) + 1e-6f);
;             bf16_t* yrow = CAT + (cur.tok0 + c) * CATW + dir * 512 + 128 * h + 4 * fq;
; #pragma unroll
;             for (int eb = 0; eb < 8; ++eb) {
;                 const u32x2 gr = pg[eb];
;                 const f32x4 y = (accO[eb] - mean) * rstd;
;                 u32x2 w; w.x = cvt_pk_bf16(silu_f(bf_lo(gr.x)) * y[0], silu_f(bf_hi(gr.x)) * y[1]); w.y = cvt_pk_bf16(silu_f(bf_lo(gr.y)) * y[2], silu_f(bf_hi(gr.y)) * y[3]);
.LBB0_808:
	v_mov_b32_e32 v88, v80
	v_mov_b32_e32 v89, v84
	v_mov_b32_e32 v90, v81
	v_mov_b32_e32 v91, v85
	v_pk_add_f32 v[88:89], v[88:89], v[90:91]
	v_mov_b32_e32 v90, v82
	v_mov_b32_e32 v91, v86
	v_mov_b32_e32 v92, v83
	v_mov_b32_e32 v93, v87
	v_pk_add_f32 v[90:91], v[90:91], v[92:93]
	v_mov_b32_e32 v92, v76
	v_pk_add_f32 v[88:89], v[88:89], v[90:91]
	v_mov_b32_e32 v90, v77
	v_mov_b32_e32 v91, v78
	v_mov_b32_e32 v93, v79
	v_pk_add_f32 v[90:91], v[90:91], v[92:93]
	v_add_f32_e32 v89, 0, v89
	v_pk_add_f32 v[90:91], v[90:91], v[90:91] op_sel_hi:[0,1]
	v_add_f32_e32 v89, v88, v89
	v_add_f32_e32 v93, v72, v73
	v_add_f32_e32 v95, v74, v75
	v_mov_b32_e32 v92, v68
	v_mov_b32_e32 v94, v69
	v_mov_b32_e32 v90, v70
	v_mov_b32_e32 v88, v71
	v_pk_add_f32 v[92:93], v[92:93], v[94:95]
	v_pk_add_f32 v[88:89], v[90:91], v[88:89]
	v_mov_b32_e32 v90, v65
	v_pk_add_f32 v[88:89], v[92:93], v[88:89]
	v_mov_b32_e32 v91, v66
	v_mov_b32_e32 v92, v64
	v_mov_b32_e32 v93, v67
	v_pk_add_f32 v[90:91], v[90:91], v[92:93]
	v_pk_add_f32 v[88:89], v[88:89], v[88:89] op_sel_hi:[0,1]
	v_pk_add_f32 v[90:91], v[90:91], v[90:91] op_sel_hi:[0,1]
	v_add_f32_e32 v93, v60, v61
	v_add_f32_e32 v95, v62, v63
	v_mov_b32_e32 v92, v56
	v_mov_b32_e32 v94, v57
	v_mov_b32_e32 v90, v58
	v_mov_b32_e32 v88, v59
	v_pk_add_f32 v[92:93], v[92:93], v[94:95]
	v_pk_add_f32 v[88:89], v[90:91], v[88:89]
	v_and_b32_e32 v90, 64, v165
	v_pk_add_f32 v[88:89], v[92:93], v[88:89]
	v_add_u32_e32 v90, 64, v90
	v_add_f32_e32 v88, v88, v89
	v_xor_b32_e32 v89, 16, v165
	v_cmp_lt_i32_e32 vcc, v89, v90
	s_mov_b32 s78, 0x800000
	s_nop 0
	v_cndmask_b32_e32 v89, v165, v89, vcc
	v_lshlrev_b32_e32 v98, 2, v89
	ds_bpermute_b32 v89, v98, v88
	s_waitcnt lgkmcnt(0)
	v_add_f32_e32 v88, v88, v89
	v_xor_b32_e32 v89, 32, v165
	v_cmp_lt_i32_e32 vcc, v89, v90
	s_nop 1
	v_cndmask_b32_e32 v89, v165, v89, vcc
	v_lshlrev_b32_e32 v99, 2, v89
	ds_bpermute_b32 v89, v99, v88
	s_waitcnt lgkmcnt(0)
	v_add_f32_e32 v100, v88, v89
	v_fmamk_f32 v85, v100, 0xbc000000, v85
	v_fmamk_f32 v81, v100, 0xbc000000, v81
	v_fmamk_f32 v87, v100, 0xbc000000, v87
	v_fmac_f32_e32 v84, 0xbc000000, v100
	v_fmamk_f32 v89, v100, 0xbc000000, v83
	v_fmac_f32_e32 v80, 0xbc000000, v100
	v_mov_b32_e32 v90, v85
	v_mov_b32_e32 v91, v81
	v_fmamk_f32 v86, v100, 0xbc000000, v86
	v_fmamk_f32 v88, v100, 0xbc000000, v82
	v_mov_b32_e32 v82, v84
	v_mov_b32_e32 v83, v80
	v_pk_mul_f32 v[90:91], v[90:91], v[90:91]
	v_mov_b32_e32 v92, v87
	v_mov_b32_e32 v93, v89
	v_pk_fma_f32 v[82:83], v[82:83], v[82:83], v[90:91]
	v_mov_b32_e32 v90, v86
	v_mov_b32_e32 v91, v88
	v_pk_mul_f32 v[92:93], v[92:93], v[92:93]
	v_fmamk_f32 v79, v100, 0xbc000000, v79
	v_pk_fma_f32 v[90:91], v[90:91], v[90:91], v[92:93]
	v_fmamk_f32 v93, v100, 0xbc000000, v77
	v_pk_add_f32 v[82:83], v[82:83], v[90:91]
	v_fmamk_f32 v92, v100, 0xbc000000, v76
	v_fmac_f32_e32 v78, 0xbc000000, v100
	v_pk_add_f32 v[90:91], v[82:83], v[82:83] op_sel_hi:[0,1]
	v_pk_mul_f32 v[76:77], v[78:79], v[78:79]
	v_pk_mul_f32 v[82:83], v[92:93], v[92:93]
	v_fmac_f32_e32 v74, 0xbc000000, v100
	v_pk_mov_b32 v[94:95], v[82:83], v[76:77] op_sel:[1,0]
	v_mov_b32_e32 v83, v77
	v_pk_add_f32 v[76:77], v[94:95], v[82:83]
	v_fmamk_f32 v82, v100, 0xbc000000, v72
	v_fmamk_f32 v83, v100, 0xbc000000, v73
	v_mul_f32_e32 v72, v82, v82
	v_pk_fma_f32 v[72:73], v[82:83], v[82:83], v[72:73] op_sel_hi:[1,1,0]
	v_fmamk_f32 v75, v100, 0xbc000000, v75
	v_mul_f32_e32 v72, v74, v74
	v_pk_add_f32 v[94:95], v[76:77], v[76:77] op_sel_hi:[0,1]
	v_pk_fma_f32 v[96:97], v[74:75], v[74:75], v[72:73] op_sel_hi:[1,1,0]
	v_fmamk_f32 v77, v100, 0xbc000000, v71
	v_fmamk_f32 v76, v100, 0xbc000000, v70
	v_fmamk_f32 v69, v100, 0xbc000000, v69
	v_fmac_f32_e32 v68, 0xbc000000, v100
	v_mul_f32_e32 v72, v68, v68
	v_mul_f32_e32 v96, v69, v69
	v_mul_f32_e32 v94, v76, v76
	v_mul_f32_e32 v90, v77, v77
	v_pk_add_f32 v[70:71], v[72:73], v[96:97]
	v_pk_add_f32 v[72:73], v[94:95], v[90:91]
	v_fmamk_f32 v67, v100, 0xbc000000, v67
	v_pk_add_f32 v[70:71], v[70:71], v[72:73]
	v_fmamk_f32 v73, v100, 0xbc000000, v65
	v_fmamk_f32 v72, v100, 0xbc000000, v64
	v_fmac_f32_e32 v66, 0xbc000000, v100
	v_pk_add_f32 v[90:91], v[70:71], v[70:71] op_sel_hi:[0,1]
	v_pk_mul_f32 v[64:65], v[66:67], v[66:67]
	v_pk_mul_f32 v[70:71], v[72:73], v[72:73]
	v_fmac_f32_e32 v62, 0xbc000000, v100
	v_pk_mov_b32 v[94:95], v[70:71], v[64:65] op_sel:[1,0]
	v_mov_b32_e32 v71, v65
	v_pk_add_f32 v[64:65], v[94:95], v[70:71]
	v_fmamk_f32 v70, v100, 0xbc000000, v60
	v_fmamk_f32 v71, v100, 0xbc000000, v61
	v_mul_f32_e32 v60, v70, v70
	v_fmamk_f32 v63, v100, 0xbc000000, v63
	v_pk_fma_f32 v[94:95], v[70:71], v[70:71], v[60:61] op_sel_hi:[1,1,0]
	v_mul_f32_e32 v60, v62, v62
	v_pk_add_f32 v[64:65], v[64:65], v[64:65] op_sel_hi:[0,1]
	v_pk_fma_f32 v[96:97], v[62:63], v[62:63], v[60:61] op_sel_hi:[1,1,0]
	v_fmamk_f32 v61, v100, 0xbc000000, v59
	v_fmamk_f32 v60, v100, 0xbc000000, v58
	v_fmamk_f32 v57, v100, 0xbc000000, v57
	v_fmac_f32_e32 v56, 0xbc000000, v100
	v_mul_f32_e32 v94, v56, v56
	v_mul_f32_e32 v96, v57, v57
	v_mul_f32_e32 v64, v60, v60
	v_mul_f32_e32 v90, v61, v61
	v_pk_add_f32 v[58:59], v[94:95], v[96:97]
	v_pk_add_f32 v[64:65], v[64:65], v[90:91]
	v_lshl_add_u64 v[90:91], s[86:87], 0, v[110:111]
	v_pk_add_f32 v[58:59], v[58:59], v[64:65]
	s_waitcnt vmcnt(7)
	v_lshlrev_b32_e32 v65, 16, v148
	v_add_f32_e32 v58, v58, v59
	ds_bpermute_b32 v59, v98, v58
	s_waitcnt lgkmcnt(0)
	v_add_f32_e32 v58, v58, v59
	ds_bpermute_b32 v59, v99, v58
	s_waitcnt lgkmcnt(0)
; __device__ __forceinline__ unsigned cvt_pk_bf16(float lo, float hi) { unsigned r; asm volatile("v_cvt_pk_bf16_f32 %0, %1, %2" : "=v"(r) : "v"(lo), "v"(hi)); return r; }
; __device__ __forceinline__ float bf_lo(unsigned u) { return __uint_as_float(u << 16); }
; __device__ __forceinline__ float bf_hi(unsigned u) { return __uint_as_float(u & 0xffff0000u); }
; __device__ __forceinline__ float silu_f(float a) { return a * __builtin_amdgcn_rcpf(1.0f + __expf(-a)); }
; __device__ __forceinline__ void retention_item(LAS unsigned char* lds, const Params& p, int item) {
;     ...
;             const float rstd = rsqrtf(vq * (1.0f / 128.0f) + 1e-6f);
;             bf16_t* yrow = CAT + (cur.tok0 + c) * CATW + dir * 512 + 128 * h + 4 * fq;
; #pragma unroll
;             for (int eb = 0; eb < 8; ++eb) {
;                 const u32x2 gr = pg[eb];
;                 const f32x4 y = (accO[eb] - mean) * rstd;
;                 u32x2 w; w.x = cvt_pk_bf16(silu_f(bf_lo(gr.x)) * y[0], silu_f(bf_hi(gr.x)) * y[1]); w.y = cvt_pk_bf16(silu_f(bf_lo(gr.y)) * y[2], silu_f(bf_hi(gr.y)) * y[3]);
;                 *(u32x2*)(yrow + 16 * eb) = w;
	v_add_f32_e32 v58, v58, v59
	v_fmamk_f32 v58, v58, 0x3c000000, v164
	v_mul_f32_e32 v59, 0x4b800000, v58
	v_cmp_gt_f32_e32 vcc, s78, v58
	s_nop 1
	v_cndmask_b32_e32 v58, v58, v59, vcc
	v_rsq_f32_e32 v58, v58
	s_nop 0
	v_mul_f32_e32 v59, 0x45800000, v58
	v_cndmask_b32_e32 v64, v58, v59, vcc
	v_mad_u64_u32 v[58:59], s[78:79], v90, s33, v[130:131]
	v_mov_b32_e32 v90, v59
	v_mad_u64_u32 v[90:91], s[78:79], v91, s33, v[90:91]
	v_mov_b32_e32 v59, v90
	v_mul_f32_e32 v90, 0xbfb8aa3b, v65
	v_and_b32_e32 v91, 0xffff0000, v148
	v_exp_f32_e32 v90, v90
	v_mul_f32_e32 v94, 0xbfb8aa3b, v91
	v_exp_f32_e32 v94, v94
	v_pk_mul_f32 v[86:87], v[86:87], v[64:65] op_sel_hi:[1,0]
	v_add_f32_e32 v90, 1.0, v90
	v_rcp_f32_e32 v90, v90
	v_add_f32_e32 v94, 1.0, v94
	v_rcp_f32_e32 v94, v94
	v_pk_mul_f32 v[84:85], v[84:85], v[64:65] op_sel_hi:[1,0]
	v_mul_f32_e32 v65, v90, v65
	v_mul_f32_e32 v65, v65, v84
	v_mul_f32_e32 v84, v94, v91
	v_lshlrev_b32_e32 v90, 16, v149
	v_and_b32_e32 v94, 0xffff0000, v149
	v_mul_f32_e32 v91, 0xbfb8aa3b, v90
	v_mul_f32_e32 v95, 0xbfb8aa3b, v94
	v_exp_f32_e32 v91, v91
	v_exp_f32_e32 v95, v95
	v_mul_f32_e32 v84, v84, v85
	v_cvt_pk_bf16_f32 v84, v65, v84
	v_add_f32_e32 v85, 1.0, v91
	v_add_f32_e32 v91, 1.0, v95
	v_rcp_f32_e32 v85, v85
	v_rcp_f32_e32 v91, v91
	s_andn2_b64 vcc, exec, s[92:93]
	v_mul_f32_e32 v65, v85, v90
	v_mul_f32_e32 v85, v91, v94
	v_mul_f32_e32 v65, v65, v86
	v_mul_f32_e32 v85, v85, v87
	v_cvt_pk_bf16_f32 v85, v65, v85
	s_waitcnt vmcnt(7)
	v_lshlrev_b32_e32 v65, 16, v150
	global_store_dwordx2 v[58:59], v[84:85], off
	v_mul_f32_e32 v84, 0xbfb8aa3b, v65
	v_and_b32_e32 v87, 0xffff0000, v150
	v_exp_f32_e32 v86, v84
	v_mul_f32_e32 v84, 0xbfb8aa3b, v87
	v_exp_f32_e32 v90, v84
	v_pk_mul_f32 v[84:85], v[88:89], v[64:65] op_sel_hi:[1,0]
	v_add_f32_e32 v86, 1.0, v86
	v_rcp_f32_e32 v86, v86
	v_add_f32_e32 v88, 1.0, v90
	v_rcp_f32_e32 v88, v88
	v_pk_mul_f32 v[80:81], v[80:81], v[64:65] op_sel_hi:[1,0]
	v_mul_f32_e32 v65, v86, v65
	v_mul_f32_e32 v65, v65, v80
	v_mul_f32_e32 v80, v88, v87
	v_lshlrev_b32_e32 v86, 16, v151
	v_and_b32_e32 v88, 0xffff0000, v151
	v_mul_f32_e32 v87, 0xbfb8aa3b, v86
	v_mul_f32_e32 v89, 0xbfb8aa3b, v88
	v_exp_f32_e32 v87, v87
	v_exp_f32_e32 v89, v89
	v_mul_f32_e32 v80, v80, v81
	v_cvt_pk_bf16_f32 v80, v65, v80
	v_add_f32_e32 v81, 1.0, v87
	v_add_f32_e32 v87, 1.0, v89
	v_rcp_f32_e32 v81, v81
	v_rcp_f32_e32 v87, v87
	v_mul_f32_e32 v65, v81, v86
	v_mul_f32_e32 v81, v87, v88
	v_mul_f32_e32 v65, v65, v84
	v_mul_f32_e32 v81, v81, v85
	v_cvt_pk_bf16_f32 v81, v65, v81
	s_waitcnt vmcnt(7)
	v_lshlrev_b32_e32 v65, 16, v152
	global_store_dwordx2 v[58:59], v[80:81], off offset:32
	v_mul_f32_e32 v80, 0xbfb8aa3b, v65
	v_and_b32_e32 v84, 0xffff0000, v152
	v_exp_f32_e32 v80, v80
	v_mul_f32_e32 v81, 0xbfb8aa3b, v84
	v_exp_f32_e32 v81, v81
	v_pk_mul_f32 v[78:79], v[78:79], v[64:65] op_sel_hi:[1,0]
	v_add_f32_e32 v80, 1.0, v80
	v_rcp_f32_e32 v85, v80
	v_add_f32_e32 v80, 1.0, v81
	v_rcp_f32_e32 v86, v80
	v_pk_mul_f32 v[80:81], v[92:93], v[64:65] op_sel_hi:[1,0]
	v_mul_f32_e32 v65, v85, v65
	v_mul_f32_e32 v65, v65, v80
	v_mul_f32_e32 v80, v86, v84
	v_lshlrev_b32_e32 v84, 16, v153
	v_mul_f32_e32 v85, 0xbfb8aa3b, v84
	v_and_b32_e32 v86, 0xffff0000, v153
	v_exp_f32_e32 v85, v85
	v_mul_f32_e32 v87, 0xbfb8aa3b, v86
	v_exp_f32_e32 v87, v87
	v_mul_f32_e32 v80, v80, v81
	v_add_f32_e32 v81, 1.0, v85
	v_rcp_f32_e32 v81, v81
	v_add_f32_e32 v85, 1.0, v87
	v_rcp_f32_e32 v85, v85
	v_cvt_pk_bf16_f32 v80, v65, v80
	v_mul_f32_e32 v65, v81, v84
	v_mul_f32_e32 v65, v65, v78
	v_mul_f32_e32 v78, v85, v86
	v_mul_f32_e32 v78, v78, v79
	v_cvt_pk_bf16_f32 v81, v65, v78
	s_waitcnt vmcnt(7)
	v_lshlrev_b32_e32 v65, 16, v154
	global_store_dwordx2 v[58:59], v[80:81], off offset:64
	v_mul_f32_e32 v78, 0xbfb8aa3b, v65
	v_and_b32_e32 v80, 0xffff0000, v154
	v_exp_f32_e32 v78, v78
	v_mul_f32_e32 v79, 0xbfb8aa3b, v80
	v_exp_f32_e32 v79, v79
	v_pk_mul_f32 v[74:75], v[74:75], v[64:65] op_sel_hi:[1,0]
	v_add_f32_e32 v78, 1.0, v78
	v_rcp_f32_e32 v81, v78
	v_add_f32_e32 v78, 1.0, v79
	v_rcp_f32_e32 v84, v78
	v_pk_mul_f32 v[78:79], v[82:83], v[64:65] op_sel_hi:[1,0]
	v_mul_f32_e32 v65, v81, v65
	v_mul_f32_e32 v65, v65, v78
	v_mul_f32_e32 v78, v84, v80
	v_lshlrev_b32_e32 v80, 16, v155
	v_mul_f32_e32 v81, 0xbfb8aa3b, v80
	v_and_b32_e32 v82, 0xffff0000, v155
	v_exp_f32_e32 v81, v81
	v_mul_f32_e32 v83, 0xbfb8aa3b, v82
	v_exp_f32_e32 v83, v83
	v_mul_f32_e32 v78, v78, v79
	v_add_f32_e32 v79, 1.0, v81
	v_rcp_f32_e32 v79, v79
	v_add_f32_e32 v81, 1.0, v83
	v_rcp_f32_e32 v81, v81
	v_cvt_pk_bf16_f32 v78, v65, v78
	v_mul_f32_e32 v65, v79, v80
	v_mul_f32_e32 v65, v65, v74
	v_mul_f32_e32 v74, v81, v82
	v_mul_f32_e32 v74, v74, v75
	v_cvt_pk_bf16_f32 v79, v65, v74
	s_waitcnt vmcnt(7)
; __device__ __forceinline__ unsigned cvt_pk_bf16(float lo, float hi) { unsigned r; asm volatile("v_cvt_pk_bf16_f32 %0, %1, %2" : "=v"(r) : "v"(lo), "v"(hi)); return r; }
; __device__ __forceinline__ float bf_lo(unsigned u) { return __uint_as_float(u << 16); }
; __device__ __forceinline__ float bf_hi(unsigned u) { return __uint_as_float(u & 0xffff0000u); }
; __device__ __forceinline__ float silu_f(float a) { return a * __builtin_amdgcn_rcpf(1.0f + __expf(-a)); }
; __device__ __forceinline__ void retention_item(LAS unsigned char* lds, const Params& p, int item) {
;     ...
;             bf16_t* yrow = CAT + (cur.tok0 + c) * CATW + dir * 512 + 128 * h + 4 * fq;
; #pragma unroll
;             for (int eb = 0; eb < 8; ++eb) {
;                 const u32x2 gr = pg[eb];
;                 const f32x4 y = (accO[eb] - mean) * rstd;
;                 u32x2 w; w.x = cvt_pk_bf16(silu_f(bf_lo(gr.x)) * y[0], silu_f(bf_hi(gr.x)) * y[1]); w.y = cvt_pk_bf16(silu_f(bf_lo(gr.y)) * y[2], silu_f(bf_hi(gr.y)) * y[3]);
;                 *(u32x2*)(yrow + 16 * eb) = w;
;             }
;             if (step + 1 < 18) {
;                 const RetStep nx = ret_step(p, step + 1, b, dir);
;                 const bf16_t* grow = P + (nx.tok0 + c) * PW + 512 + dir * 512 + 128 * h + 4 * fq;
; #pragma unroll
;                 for (int eb = 0; eb < 8; ++eb) pg[eb] = *(const u32x2*)(grow + 16 * eb);
;             }
	v_lshlrev_b32_e32 v65, 16, v156
	global_store_dwordx2 v[58:59], v[78:79], off offset:96
	v_mul_f32_e32 v74, 0xbfb8aa3b, v65
	v_and_b32_e32 v79, 0xffff0000, v156
	v_exp_f32_e32 v78, v74
	v_mul_f32_e32 v74, 0xbfb8aa3b, v79
	v_exp_f32_e32 v80, v74
	v_pk_mul_f32 v[74:75], v[76:77], v[64:65] op_sel_hi:[1,0]
	v_add_f32_e32 v76, 1.0, v78
	v_rcp_f32_e32 v76, v76
	v_add_f32_e32 v77, 1.0, v80
	v_rcp_f32_e32 v77, v77
	v_pk_mul_f32 v[68:69], v[68:69], v[64:65] op_sel_hi:[1,0]
	v_mul_f32_e32 v65, v76, v65
	v_lshlrev_b32_e32 v76, 16, v157
	v_and_b32_e32 v78, 0xffff0000, v157
	v_mul_f32_e32 v65, v65, v68
	v_mul_f32_e32 v68, v77, v79
	v_mul_f32_e32 v77, 0xbfb8aa3b, v76
	v_mul_f32_e32 v79, 0xbfb8aa3b, v78
	v_exp_f32_e32 v77, v77
	v_exp_f32_e32 v79, v79
	v_mul_f32_e32 v68, v68, v69
	v_cvt_pk_bf16_f32 v68, v65, v68
	v_add_f32_e32 v69, 1.0, v77
	v_add_f32_e32 v77, 1.0, v79
	v_rcp_f32_e32 v69, v69
	v_rcp_f32_e32 v77, v77
	v_mul_f32_e32 v65, v69, v76
	v_mul_f32_e32 v69, v77, v78
	v_mul_f32_e32 v65, v65, v74
	v_mul_f32_e32 v69, v69, v75
	v_cvt_pk_bf16_f32 v69, v65, v69
	s_waitcnt vmcnt(7)
	v_lshlrev_b32_e32 v65, 16, v158
	global_store_dwordx2 v[58:59], v[68:69], off offset:128
	v_mul_f32_e32 v68, 0xbfb8aa3b, v65
	v_and_b32_e32 v74, 0xffff0000, v158
	v_exp_f32_e32 v68, v68
	v_mul_f32_e32 v69, 0xbfb8aa3b, v74
	v_exp_f32_e32 v69, v69
	v_pk_mul_f32 v[66:67], v[66:67], v[64:65] op_sel_hi:[1,0]
	v_add_f32_e32 v68, 1.0, v68
	v_rcp_f32_e32 v75, v68
	v_add_f32_e32 v68, 1.0, v69
	v_rcp_f32_e32 v76, v68
	v_pk_mul_f32 v[68:69], v[72:73], v[64:65] op_sel_hi:[1,0]
	v_mul_f32_e32 v65, v75, v65
	v_lshlrev_b32_e32 v72, 16, v159
	v_mul_f32_e32 v65, v65, v68
	v_mul_f32_e32 v68, v76, v74
	v_mul_f32_e32 v73, 0xbfb8aa3b, v72
	v_and_b32_e32 v74, 0xffff0000, v159
	v_exp_f32_e32 v73, v73
	v_mul_f32_e32 v75, 0xbfb8aa3b, v74
	v_exp_f32_e32 v75, v75
	v_mul_f32_e32 v68, v68, v69
	v_add_f32_e32 v69, 1.0, v73
	v_rcp_f32_e32 v69, v69
	v_add_f32_e32 v73, 1.0, v75
	v_rcp_f32_e32 v73, v73
	v_cvt_pk_bf16_f32 v68, v65, v68
	v_mul_f32_e32 v65, v69, v72
	v_mul_f32_e32 v65, v65, v66
	v_mul_f32_e32 v66, v73, v74
	v_mul_f32_e32 v66, v66, v67
	v_cvt_pk_bf16_f32 v69, v65, v66
	s_waitcnt vmcnt(7)
	v_lshlrev_b32_e32 v65, 16, v160
	global_store_dwordx2 v[58:59], v[68:69], off offset:160
	v_mul_f32_e32 v66, 0xbfb8aa3b, v65
	v_and_b32_e32 v68, 0xffff0000, v160
	v_exp_f32_e32 v66, v66
	v_mul_f32_e32 v67, 0xbfb8aa3b, v68
	v_exp_f32_e32 v67, v67
	v_pk_mul_f32 v[62:63], v[62:63], v[64:65] op_sel_hi:[1,0]
	v_add_f32_e32 v66, 1.0, v66
	v_rcp_f32_e32 v69, v66
	v_add_f32_e32 v66, 1.0, v67
	v_rcp_f32_e32 v72, v66
	v_pk_mul_f32 v[66:67], v[70:71], v[64:65] op_sel_hi:[1,0]
	v_mul_f32_e32 v65, v69, v65
	v_mul_f32_e32 v65, v65, v66
	v_mul_f32_e32 v66, v72, v68
	v_lshlrev_b32_e32 v68, 16, v161
	v_mul_f32_e32 v69, 0xbfb8aa3b, v68
	v_and_b32_e32 v70, 0xffff0000, v161
	v_exp_f32_e32 v69, v69
	v_mul_f32_e32 v71, 0xbfb8aa3b, v70
	v_exp_f32_e32 v71, v71
	v_mul_f32_e32 v66, v66, v67
	v_add_f32_e32 v67, 1.0, v69
	v_rcp_f32_e32 v67, v67
	v_add_f32_e32 v69, 1.0, v71
	v_rcp_f32_e32 v69, v69
	v_cvt_pk_bf16_f32 v66, v65, v66
	v_mul_f32_e32 v65, v67, v68
	v_mul_f32_e32 v62, v65, v62
	v_mul_f32_e32 v65, v69, v70
	v_mul_f32_e32 v63, v65, v63
	v_cvt_pk_bf16_f32 v67, v62, v63
	s_waitcnt vmcnt(7)
	v_lshlrev_b32_e32 v62, 16, v146
	v_mul_f32_e32 v63, 0xbfb8aa3b, v62
	v_and_b32_e32 v65, 0xffff0000, v146
	global_store_dwordx2 v[58:59], v[66:67], off offset:192
	v_exp_f32_e32 v63, v63
	v_mul_f32_e32 v66, 0xbfb8aa3b, v65
	v_exp_f32_e32 v66, v66
	v_pk_mul_f32 v[56:57], v[56:57], v[64:65] op_sel_hi:[1,0]
	v_add_f32_e32 v63, 1.0, v63
	v_rcp_f32_e32 v63, v63
	v_add_f32_e32 v66, 1.0, v66
	v_rcp_f32_e32 v66, v66
	v_pk_mul_f32 v[60:61], v[60:61], v[64:65] op_sel_hi:[1,0]
	v_mul_f32_e32 v62, v63, v62
	v_lshlrev_b32_e32 v63, 16, v147
	v_mul_f32_e32 v56, v62, v56
	v_mul_f32_e32 v62, v66, v65
	v_mul_f32_e32 v64, 0xbfb8aa3b, v63
	v_and_b32_e32 v65, 0xffff0000, v147
	v_exp_f32_e32 v64, v64
	v_mul_f32_e32 v66, 0xbfb8aa3b, v65
	v_exp_f32_e32 v66, v66
	v_mul_f32_e32 v57, v62, v57
	v_add_f32_e32 v62, 1.0, v64
	v_rcp_f32_e32 v62, v62
	v_add_f32_e32 v64, 1.0, v66
	v_rcp_f32_e32 v64, v64
	v_cvt_pk_bf16_f32 v56, v56, v57
	v_mul_f32_e32 v57, v62, v63
	v_mul_f32_e32 v57, v57, v60
	v_mul_f32_e32 v60, v64, v65
	v_mul_f32_e32 v60, v60, v61
	v_cvt_pk_bf16_f32 v57, v57, v60
	global_store_dwordx2 v[58:59], v[56:57], off offset:224
	s_cbranch_vccnz .LBB0_774
	s_add_i32 s80, s95, -1
	s_add_i32 s81, s94, 16
	s_and_b64 s[78:79], s[2:3], exec
	s_cselect_b32 s78, s80, s81
	s_lshl_b32 s90, s78, 7
	v_lshl_add_u64 v[56:57], v[132:133], 0, s[90:91]
	v_mad_u64_u32 v[58:59], s[78:79], v56, s33, v[144:145]
	v_mad_i32_i24 v59, v57, s33, v59
	global_load_dwordx2 v[148:149], v[58:59], off offset:1024
	global_load_dwordx2 v[150:151], v[58:59], off offset:1056
	global_load_dwordx2 v[152:153], v[58:59], off offset:1088
	global_load_dwordx2 v[154:155], v[58:59], off offset:1120
	global_load_dwordx2 v[156:157], v[58:59], off offset:1152
	global_load_dwordx2 v[158:159], v[58:59], off offset:1184
	global_load_dwordx2 v[160:161], v[58:59], off offset:1216
	global_load_dwordx2 v[146:147], v[58:59], off offset:1248
	s_branch .LBB0_774
